# v73 + instruction selection: score-accumulator init splat uses v_mov_b64 (15 -> 8 VALU on the barrier-to-first-MFMA path) in the three attention loops
# speedup vs baseline: 1.0082x; 1.0028x over previous
; #define MFMA32(a, b, c) __builtin_amdgcn_mfma_f32_32x32x16_bf16((a), (b), (c), 0, 0, 0)
; template <int DQK, int KROW, bool BIAS, bool MAPS2>
; DI void attn_core(const int t, const u16* __restrict__ Q, int ldq, const u16* __restrict__ Kp, int ldk, const u16* __restrict__ Vt, int q0,
;                   char* lds, const float* lut, float b31, f32x16 (&o)[4], float& l_out) {
;     ...
;     const bool live = (kt << 6) <= wq0 + 31;
;     if (live) {
;       const int k0 = kt << 6;
;       const bool far = BIAS && (wq0 - (k0 + 63) >= 128);
;       const float init = (far ? b31 : 0.f) - m_run;
; #pragma unroll
;       for (int k2 = 0; k2 < 2; ++k2)
; #pragma unroll
;         for (int i = 0; i < 16; ++i) s[k2][i] = init;
;       {
;         constexpr int QBS = (NKS > 4) ? 2 : 4, NBT = NKS / QBS;
;         bf16x8 kfb[2][QBS][2];
;         const char* kbase = lds + (kt & 1) * AT_KBUF + r * KS + hf * 16 + map * (DQK * 2);
; #pragma unroll
;         for (int jq = 0; jq < QBS; ++jq)
; #pragma unroll
;           for (int k2 = 0; k2 < 2; ++k2) kfb[0][jq][k2] = *(const bf16x8*)(kbase + 32 * k2 * KS + jq * 32);
; #pragma unroll
;         for (int b = 0; b < NBT; ++b) {
;           if (b + 1 < NBT) {
; #pragma unroll
;             for (int jq = 0; jq < QBS; ++jq)
; #pragma unroll
;               for (int k2 = 0; k2 < 2; ++k2) kfb[(b + 1) & 1][jq][k2] = *(const bf16x8*)(kbase + 32 * k2 * KS + ((b + 1) * QBS + jq) * 32);
;           }
;           __builtin_amdgcn_sched_barrier(0);
;           __builtin_amdgcn_s_setprio(1);
; #pragma unroll
;           for (int jq = 0; jq < QBS; ++jq)
; #pragma unroll
;             for (int k2 = 0; k2 < 2; ++k2) s[k2] = MFMA32(kfb[b & 1][jq][k2], qf[b * QBS + jq], s[k2]);
;           __builtin_amdgcn_s_setprio(0);
;           __builtin_amdgcn_sched_barrier(0);
;         }
;       }
;       if (BIAS && !far) {
; #pragma unroll
;         for (int k2 = 0; k2 < 2; ++k2)
; #pragma unroll
;           for (int i = 0; i < 16; ++i) {
;             const int key = k0 + 32 * k2 + (i & 3) + 8 * (i >> 2) + 4 * hf;
;             int d = qrow - key; d = d < 0 ? 0 : (d > 128 ? 128 : d);
;             s[k2][i] += lut[d];
;           }
;       }
.LBB0_235:
	v_cmp_le_i32_e32 vcc, s90, v155
	s_and_saveexec_b64 s[92:93], vcc
	s_cbranch_execz .LBB0_243
	s_cmp_eq_u32 s96, 0
	s_cselect_b32 s97, 0xff800000, s6
	s_movk_i32 s0, 0x80
	v_cmp_gt_i32_e32 vcc, s0, v159
	s_movk_i32 s0, 0x7f
	v_cmp_lt_i32_e64 s[0:1], s0, v159
	s_and_b32 s91, s96, 1
	s_nop 0
	v_cndmask_b32_e64 v0, 0, v152, s[0:1]
	s_mul_i32 s0, s91, 0x6400
	v_sub_f32_e32 v80, v0, v161
	v_add_u32_e32 v0, s0, v156
	ds_read_b128 v[2:5], v0 offset:8704
	ds_read_b128 v[6:9], v0
	ds_read_b128 v[10:13], v0 offset:32
	ds_read_b128 v[162:165], v0 offset:8736
	ds_read_b128 v[166:169], v0 offset:64
	ds_read_b128 v[170:173], v0 offset:8768
	ds_read_b128 v[174:177], v0 offset:96
	ds_read_b128 v[178:181], v0 offset:8800
	s_setprio 1
	v_mov_b32_e32 v81, v80
	v_mov_b64_e32 v[82:83], v[80:81]
	v_mov_b64_e32 v[84:85], v[80:81]
	v_mov_b64_e32 v[86:87], v[80:81]
	v_mov_b64_e32 v[88:89], v[80:81]
	v_mov_b64_e32 v[90:91], v[80:81]
	v_mov_b64_e32 v[92:93], v[80:81]
	v_mov_b64_e32 v[94:95], v[80:81]
	s_waitcnt lgkmcnt(6)
	s_nop 0
	v_mfma_f32_32x32x16_bf16 v[96:111], v[6:9], v[112:115], v[80:95]
	v_mfma_f32_32x32x16_bf16 v[80:95], v[2:5], v[112:115], v[80:95]
	s_waitcnt lgkmcnt(5)
	v_mfma_f32_32x32x16_bf16 v[96:111], v[10:13], v[116:119], v[96:111]
	s_waitcnt lgkmcnt(4)
	v_mfma_f32_32x32x16_bf16 v[80:95], v[162:165], v[116:119], v[80:95]
	s_waitcnt lgkmcnt(3)
	v_mfma_f32_32x32x16_bf16 v[96:111], v[166:169], v[120:123], v[96:111]
	s_waitcnt lgkmcnt(2)
	v_mfma_f32_32x32x16_bf16 v[80:95], v[170:173], v[120:123], v[80:95]
	s_waitcnt lgkmcnt(1)
	v_mfma_f32_32x32x16_bf16 v[96:111], v[174:177], v[124:127], v[96:111]
	s_waitcnt lgkmcnt(0)
	v_mfma_f32_32x32x16_bf16 v[80:95], v[178:181], v[124:127], v[80:95]
	s_setprio 0
	s_and_saveexec_b64 s[0:1], vcc
	s_cbranch_execz .LBB0_238
	v_add_u32_e32 v0, v160, v159
	v_lshlrev_b32_e32 v0, 2, v0
	v_add_u32_e32 v0, 0x16178, v0
	ds_read2_b32 v[2:3], v0 offset0:63 offset1:62
	ds_read2_b32 v[4:5], v0 offset0:61 offset1:60
	ds_read2_b32 v[6:7], v0 offset0:55 offset1:54
	ds_read2_b32 v[8:9], v0 offset0:53 offset1:52
	ds_read2_b32 v[10:11], v0 offset0:47 offset1:46
	ds_read2_b32 v[12:13], v0 offset0:45 offset1:44
	ds_read2_b32 v[14:15], v0 offset0:39 offset1:38
	ds_read2_b32 v[162:163], v0 offset0:37 offset1:36
	ds_read2_b32 v[164:165], v0 offset0:31 offset1:30
	ds_read2_b32 v[166:167], v0 offset0:29 offset1:28
	ds_read2_b32 v[168:169], v0 offset0:23 offset1:22
	ds_read2_b32 v[170:171], v0 offset0:21 offset1:20
	ds_read2_b32 v[172:173], v0 offset0:15 offset1:14
	ds_read2_b32 v[174:175], v0 offset0:13 offset1:12
	ds_read2_b32 v[176:177], v0 offset0:7 offset1:6
	ds_read2_b32 v[178:179], v0 offset0:5 offset1:4
	s_waitcnt lgkmcnt(8)
	v_pk_add_f32 v[108:109], v[108:109], v[14:15]
	v_pk_add_f32 v[110:111], v[110:111], v[162:163]
	v_pk_add_f32 v[106:107], v[106:107], v[12:13]
	v_pk_add_f32 v[104:105], v[104:105], v[10:11]
	v_pk_add_f32 v[102:103], v[102:103], v[8:9]
	v_pk_add_f32 v[100:101], v[100:101], v[6:7]
	v_pk_add_f32 v[98:99], v[98:99], v[4:5]
	v_pk_add_f32 v[96:97], v[96:97], v[2:3]
	s_waitcnt lgkmcnt(0)
	v_pk_add_f32 v[94:95], v[94:95], v[178:179]
	v_pk_add_f32 v[92:93], v[92:93], v[176:177]
	v_pk_add_f32 v[90:91], v[90:91], v[174:175]
	v_pk_add_f32 v[88:89], v[88:89], v[172:173]
	v_pk_add_f32 v[86:87], v[86:87], v[170:171]
	v_pk_add_f32 v[84:85], v[84:85], v[168:169]
	v_pk_add_f32 v[82:83], v[82:83], v[166:167]
	v_pk_add_f32 v[80:81], v[80:81], v[164:165]

; #define MFMA32(a, b, c) __builtin_amdgcn_mfma_f32_32x32x16_bf16((a), (b), (c), 0, 0, 0)
; template <int DQK, int KROW, bool BIAS, bool MAPS2>
; DI void attn_core(const int t, const u16* __restrict__ Q, int ldq, const u16* __restrict__ Kp, int ldk, const u16* __restrict__ Vt, int q0,
;                   char* lds, const float* lut, float b31, f32x16 (&o)[4], float& l_out) {
;     ...
;     const bool live = (kt << 6) <= wq0 + 31;
;     if (live) {
;       const int k0 = kt << 6;
;       const bool far = BIAS && (wq0 - (k0 + 63) >= 128);
;       const float init = (far ? b31 : 0.f) - m_run;
; #pragma unroll
;       for (int k2 = 0; k2 < 2; ++k2)
; #pragma unroll
;         for (int i = 0; i < 16; ++i) s[k2][i] = init;
;       {
;         constexpr int QBS = (NKS > 4) ? 2 : 4, NBT = NKS / QBS;
;         bf16x8 kfb[2][QBS][2];
;         const char* kbase = lds + (kt & 1) * AT_KBUF + r * KS + hf * 16 + map * (DQK * 2);
; #pragma unroll
;         for (int jq = 0; jq < QBS; ++jq)
; #pragma unroll
;           for (int k2 = 0; k2 < 2; ++k2) kfb[0][jq][k2] = *(const bf16x8*)(kbase + 32 * k2 * KS + jq * 32);
; #pragma unroll
;         for (int b = 0; b < NBT; ++b) {
;           if (b + 1 < NBT) {
; #pragma unroll
;             for (int jq = 0; jq < QBS; ++jq)
; #pragma unroll
;               for (int k2 = 0; k2 < 2; ++k2) kfb[(b + 1) & 1][jq][k2] = *(const bf16x8*)(kbase + 32 * k2 * KS + ((b + 1) * QBS + jq) * 32);
;           }
;           __builtin_amdgcn_sched_barrier(0);
;           __builtin_amdgcn_s_setprio(1);
; #pragma unroll
;           for (int jq = 0; jq < QBS; ++jq)
; #pragma unroll
;             for (int k2 = 0; k2 < 2; ++k2) s[k2] = MFMA32(kfb[b & 1][jq][k2], qf[b * QBS + jq], s[k2]);
;           __builtin_amdgcn_s_setprio(0);
;           __builtin_amdgcn_sched_barrier(0);
;         }
;       }
;     ...
;       if (k0 + 63 > wq0) {
.LBB0_256:
	s_add_i32 s0, s4, 0xffffff80
	v_cmp_le_i32_e32 vcc, s0, v177
	s_and_saveexec_b64 s[90:91], vcc
	s_cbranch_execz .LBB0_262
	s_cmp_eq_u32 s93, 0
	s_cselect_b32 s97, 0xff800000, s6
	s_and_b32 s92, s93, 1
	s_mul_i32 s0, s92, 0x6400
	v_add_u32_e32 v181, s0, v178
	ds_read_b128 v[182:185], v181
	ds_read_b128 v[186:189], v181 offset:32
	ds_read_b128 v[190:193], v181 offset:12800
	ds_read_b128 v[194:197], v181 offset:12832
	ds_read_b128 v[198:201], v181 offset:64
	ds_read_b128 v[202:205], v181 offset:96
	ds_read_b128 v[206:209], v181 offset:12864
	ds_read_b128 v[210:213], v181 offset:12896
	v_sub_f32_e32 v66, 0, v180
	s_setprio 1
	v_mov_b32_e32 v67, v66
	v_mov_b64_e32 v[68:69], v[66:67]
	v_mov_b64_e32 v[70:71], v[66:67]
	v_mov_b64_e32 v[72:73], v[66:67]
	v_mov_b64_e32 v[74:75], v[66:67]
	v_mov_b64_e32 v[76:77], v[66:67]
	v_mov_b64_e32 v[78:79], v[66:67]
	v_mov_b64_e32 v[80:81], v[66:67]
	s_waitcnt vmcnt(16) lgkmcnt(7)
	s_nop 0
	v_mfma_f32_32x32x16_bf16 v[82:97], v[182:185], v[98:101], v[66:81]
	s_waitcnt lgkmcnt(5)
	v_mfma_f32_32x32x16_bf16 v[66:81], v[190:193], v[98:101], v[66:81]
	s_waitcnt vmcnt(15)
	v_mfma_f32_32x32x16_bf16 v[82:97], v[186:189], v[102:105], v[82:97]
	s_waitcnt lgkmcnt(4)
	v_mfma_f32_32x32x16_bf16 v[66:81], v[194:197], v[102:105], v[66:81]
	s_setprio 0
	ds_read_b128 v[182:185], v181 offset:128
	ds_read_b128 v[186:189], v181 offset:160
	ds_read_b128 v[190:193], v181 offset:12928
	ds_read_b128 v[194:197], v181 offset:12960
	s_setprio 1
	s_waitcnt vmcnt(14) lgkmcnt(7)
	v_mfma_f32_32x32x16_bf16 v[82:97], v[198:201], v[106:109], v[82:97]
	s_waitcnt lgkmcnt(5)
	v_mfma_f32_32x32x16_bf16 v[66:81], v[206:209], v[106:109], v[66:81]
	s_waitcnt vmcnt(13)
	v_mfma_f32_32x32x16_bf16 v[82:97], v[202:205], v[110:113], v[82:97]
	s_waitcnt lgkmcnt(4)
	v_mfma_f32_32x32x16_bf16 v[66:81], v[210:213], v[110:113], v[66:81]
	s_setprio 0
	ds_read_b128 v[198:201], v181 offset:192
	ds_read_b128 v[202:205], v181 offset:224
	ds_read_b128 v[206:209], v181 offset:12992
	ds_read_b128 v[210:213], v181 offset:13024
	s_setprio 1
	s_waitcnt vmcnt(12) lgkmcnt(7)
	v_mfma_f32_32x32x16_bf16 v[82:97], v[182:185], v[114:117], v[82:97]
	s_waitcnt lgkmcnt(5)
	v_mfma_f32_32x32x16_bf16 v[66:81], v[190:193], v[114:117], v[66:81]
	s_waitcnt vmcnt(11)
	v_mfma_f32_32x32x16_bf16 v[82:97], v[186:189], v[118:121], v[82:97]
	s_waitcnt lgkmcnt(4)
	v_mfma_f32_32x32x16_bf16 v[66:81], v[194:197], v[118:121], v[66:81]
	s_setprio 0
	ds_read_b128 v[182:185], v181 offset:256
	ds_read_b128 v[186:189], v181 offset:288
	ds_read_b128 v[190:193], v181 offset:13056
	ds_read_b128 v[194:197], v181 offset:13088
	s_setprio 1
	s_waitcnt vmcnt(10) lgkmcnt(7)
	v_mfma_f32_32x32x16_bf16 v[82:97], v[198:201], v[122:125], v[82:97]
	s_waitcnt lgkmcnt(5)
	v_mfma_f32_32x32x16_bf16 v[66:81], v[206:209], v[122:125], v[66:81]
	s_waitcnt vmcnt(9)
	v_mfma_f32_32x32x16_bf16 v[82:97], v[202:205], v[126:129], v[82:97]
	s_waitcnt lgkmcnt(4)
	v_mfma_f32_32x32x16_bf16 v[66:81], v[210:213], v[126:129], v[66:81]
	s_setprio 0
	ds_read_b128 v[198:201], v181 offset:320
	ds_read_b128 v[202:205], v181 offset:352
	ds_read_b128 v[206:209], v181 offset:13120
	ds_read_b128 v[210:213], v181 offset:13152
	s_setprio 1
	s_waitcnt vmcnt(8) lgkmcnt(7)
	v_mfma_f32_32x32x16_bf16 v[82:97], v[182:185], v[130:133], v[82:97]
	s_waitcnt lgkmcnt(5)
	v_mfma_f32_32x32x16_bf16 v[66:81], v[190:193], v[130:133], v[66:81]
	s_waitcnt vmcnt(7)
	v_mfma_f32_32x32x16_bf16 v[82:97], v[186:189], v[134:137], v[82:97]
	s_waitcnt lgkmcnt(4)
	v_mfma_f32_32x32x16_bf16 v[66:81], v[194:197], v[134:137], v[66:81]
	s_setprio 0
	s_setprio 1
	s_waitcnt vmcnt(6) lgkmcnt(3)
	v_mfma_f32_32x32x16_bf16 v[82:97], v[198:201], v[138:141], v[82:97]
	s_waitcnt lgkmcnt(1)
	v_mfma_f32_32x32x16_bf16 v[66:81], v[206:209], v[138:141], v[66:81]
	s_waitcnt vmcnt(5)
	v_mfma_f32_32x32x16_bf16 v[82:97], v[202:205], v[142:145], v[82:97]
	s_waitcnt lgkmcnt(0)
	v_mfma_f32_32x32x16_bf16 v[66:81], v[210:213], v[142:145], v[66:81]
	s_setprio 0
	s_add_i32 s0, s4, 0xffffffbf
	v_cmp_gt_i32_e32 vcc, s0, v167
	s_and_saveexec_b64 s[0:1], vcc
	s_cbranch_execz .LBB0_259
; template <int DQK, int KROW, bool BIAS, bool MAPS2>
; DI void attn_core(const int t, const u16* __restrict__ Q, int ldq, const u16* __restrict__ Kp, int ldk, const u16* __restrict__ Vt, int q0,
;                   char* lds, const float* lut, float b31, f32x16 (&o)[4], float& l_out) {
;     ...
;       if (k0 + 63 > wq0) {
; #pragma unroll
;         for (int k2 = 0; k2 < 2; ++k2)
; #pragma unroll
;           for (int i = 0; i < 16; ++i) {
;             const int key = k0 + 32 * k2 + (i & 3) + 8 * (i >> 2) + 4 * hf;
;             if (key > qrow) s[k2][i] = -INFINITY;
;           }
;       }
	v_add_u32_e32 v181, s4, v176
	v_add_u32_e32 v182, 0xffffff80, v181
	v_cmp_gt_i32_e32 vcc, v182, v170
	s_nop 1
	v_cndmask_b32_e32 v183, v82, v230, vcc
	v_cmp_lt_i32_e32 vcc, v182, v170
	v_add_u32_e32 v182, 0xffffff82, v181
	s_nop 0
	v_cndmask_b32_e32 v82, v183, v82, vcc
	v_cndmask_b32_e32 v83, v230, v83, vcc
	v_cmp_le_i32_e32 vcc, v182, v170
	v_add_u32_e32 v182, 0xffffff83, v181
	s_nop 0
	v_cndmask_b32_e32 v84, v230, v84, vcc
	v_cmp_le_i32_e32 vcc, v182, v170
	v_add_u32_e32 v182, 0xffffff88, v181
	s_nop 0
	v_cndmask_b32_e32 v85, v230, v85, vcc
	v_cmp_le_i32_e32 vcc, v182, v170
	v_add_u32_e32 v182, 0xffffff89, v181
	s_nop 0
	v_cndmask_b32_e32 v86, v230, v86, vcc
	v_cmp_le_i32_e32 vcc, v182, v170
	v_add_u32_e32 v182, 0xffffff8a, v181
	s_nop 0
	v_cndmask_b32_e32 v87, v230, v87, vcc
	v_cmp_le_i32_e32 vcc, v182, v170
	v_add_u32_e32 v182, 0xffffff8b, v181
	s_nop 0
	v_cndmask_b32_e32 v88, v230, v88, vcc
	v_cmp_le_i32_e32 vcc, v182, v170
	v_add_u32_e32 v182, 0xffffff90, v181
	s_nop 0
	v_cndmask_b32_e32 v89, v230, v89, vcc
	v_cmp_le_i32_e32 vcc, v182, v170
	v_add_u32_e32 v182, 0xffffff91, v181
	s_nop 0
	v_cndmask_b32_e32 v90, v230, v90, vcc
	v_cmp_le_i32_e32 vcc, v182, v170
	v_add_u32_e32 v182, 0xffffff92, v181
	s_nop 0
	v_cndmask_b32_e32 v91, v230, v91, vcc
	v_cmp_le_i32_e32 vcc, v182, v170
	v_add_u32_e32 v182, 0xffffff93, v181
	s_nop 0
	v_cndmask_b32_e32 v92, v230, v92, vcc
	v_cmp_le_i32_e32 vcc, v182, v170
	v_add_u32_e32 v182, 0xffffff98, v181
	s_nop 0
	v_cndmask_b32_e32 v93, v230, v93, vcc
	v_cmp_le_i32_e32 vcc, v182, v170
	v_add_u32_e32 v182, 0xffffff99, v181
	s_nop 0
	v_cndmask_b32_e32 v94, v230, v94, vcc
	v_cmp_le_i32_e32 vcc, v182, v170
	v_add_u32_e32 v182, 0xffffff9a, v181
	s_nop 0
	v_cndmask_b32_e32 v95, v230, v95, vcc
	v_cmp_le_i32_e32 vcc, v182, v170
	v_add_u32_e32 v182, 0xffffff9b, v181
	s_nop 0
	v_cndmask_b32_e32 v96, v230, v96, vcc
	v_cmp_le_i32_e32 vcc, v182, v170
	v_add_u32_e32 v182, 0xffffffa0, v181
	s_nop 0
	v_cndmask_b32_e32 v97, v230, v97, vcc
	v_cmp_le_i32_e32 vcc, v182, v170
	v_add_u32_e32 v182, 0xffffffa1, v181
	s_nop 0
	v_cndmask_b32_e32 v66, v230, v66, vcc
	v_cmp_le_i32_e32 vcc, v182, v170
	v_add_u32_e32 v182, 0xffffffa2, v181
	s_nop 0
	v_cndmask_b32_e32 v67, v230, v67, vcc
	v_cmp_le_i32_e32 vcc, v182, v170
	v_add_u32_e32 v182, 0xffffffa3, v181
	s_nop 0
	v_cndmask_b32_e32 v68, v230, v68, vcc
	v_cmp_le_i32_e32 vcc, v182, v170
	v_add_u32_e32 v182, 0xffffffa8, v181
	s_nop 0
	v_cndmask_b32_e32 v69, v230, v69, vcc
	v_cmp_le_i32_e32 vcc, v182, v170
	v_add_u32_e32 v182, 0xffffffa9, v181
	s_nop 0
	v_cndmask_b32_e32 v70, v230, v70, vcc
	v_cmp_le_i32_e32 vcc, v182, v170
	v_add_u32_e32 v182, 0xffffffaa, v181
	s_nop 0
	v_cndmask_b32_e32 v71, v230, v71, vcc
	v_cmp_le_i32_e32 vcc, v182, v170
	v_add_u32_e32 v182, 0xffffffab, v181
	s_nop 0
	v_cndmask_b32_e32 v72, v230, v72, vcc
	v_cmp_le_i32_e32 vcc, v182, v170
	v_add_u32_e32 v182, 0xffffffb0, v181
	s_nop 0
	v_cndmask_b32_e32 v73, v230, v73, vcc
	v_cmp_le_i32_e32 vcc, v182, v170
	v_add_u32_e32 v182, 0xffffffb1, v181
	s_nop 0
	v_cndmask_b32_e32 v74, v230, v74, vcc
	v_cmp_le_i32_e32 vcc, v182, v170
	v_add_u32_e32 v182, 0xffffffb2, v181
	s_nop 0
	v_cndmask_b32_e32 v75, v230, v75, vcc
	v_cmp_le_i32_e32 vcc, v182, v170
	v_add_u32_e32 v182, 0xffffffb3, v181
	s_nop 0
	v_cndmask_b32_e32 v76, v230, v76, vcc
	v_cmp_le_i32_e32 vcc, v182, v170
	v_add_u32_e32 v182, 0xffffffb8, v181
	s_nop 0
	v_cndmask_b32_e32 v77, v230, v77, vcc
	v_cmp_le_i32_e32 vcc, v182, v170
	v_add_u32_e32 v182, 0xffffffb9, v181
	s_nop 0
	v_cndmask_b32_e32 v78, v230, v78, vcc
	v_cmp_le_i32_e32 vcc, v182, v170
	v_add_u32_e32 v182, 0xffffffba, v181
	v_add_u32_e32 v181, 0xffffffbb, v181
	v_cndmask_b32_e32 v79, v230, v79, vcc
	v_cmp_le_i32_e32 vcc, v182, v170
	s_nop 1
	v_cndmask_b32_e32 v80, v230, v80, vcc
	v_cmp_le_i32_e32 vcc, v181, v170
	s_nop 1
	v_cndmask_b32_e32 v81, v230, v81, vcc

; #define MFMA32(a, b, c) __builtin_amdgcn_mfma_f32_32x32x16_bf16((a), (b), (c), 0, 0, 0)
; template <int DQK, int KROW, bool BIAS, bool MAPS2>
; DI void attn_core(const int t, const u16* __restrict__ Q, int ldq, const u16* __restrict__ Kp, int ldk, const u16* __restrict__ Vt, int q0,
;                   char* lds, const float* lut, float b31, f32x16 (&o)[4], float& l_out) {
;     ...
;     const bool live = (kt << 6) <= wq0 + 31;
;     if (live) {
;       const int k0 = kt << 6;
;       const bool far = BIAS && (wq0 - (k0 + 63) >= 128);
;       const float init = (far ? b31 : 0.f) - m_run;
; #pragma unroll
;       for (int k2 = 0; k2 < 2; ++k2)
; #pragma unroll
;         for (int i = 0; i < 16; ++i) s[k2][i] = init;
;       {
;         constexpr int QBS = (NKS > 4) ? 2 : 4, NBT = NKS / QBS;
;         bf16x8 kfb[2][QBS][2];
;         const char* kbase = lds + (kt & 1) * AT_KBUF + r * KS + hf * 16 + map * (DQK * 2);
; #pragma unroll
;         for (int jq = 0; jq < QBS; ++jq)
; #pragma unroll
;           for (int k2 = 0; k2 < 2; ++k2) kfb[0][jq][k2] = *(const bf16x8*)(kbase + 32 * k2 * KS + jq * 32);
; #pragma unroll
;         for (int b = 0; b < NBT; ++b) {
;           if (b + 1 < NBT) {
; #pragma unroll
;             for (int jq = 0; jq < QBS; ++jq)
; #pragma unroll
;               for (int k2 = 0; k2 < 2; ++k2) kfb[(b + 1) & 1][jq][k2] = *(const bf16x8*)(kbase + 32 * k2 * KS + ((b + 1) * QBS + jq) * 32);
;           }
;           __builtin_amdgcn_sched_barrier(0);
;           __builtin_amdgcn_s_setprio(1);
; #pragma unroll
;           for (int jq = 0; jq < QBS; ++jq)
; #pragma unroll
;             for (int k2 = 0; k2 < 2; ++k2) s[k2] = MFMA32(kfb[b & 1][jq][k2], qf[b * QBS + jq], s[k2]);
;           __builtin_amdgcn_s_setprio(0);
;           __builtin_amdgcn_sched_barrier(0);
;         }
;       }
;     ...
;       if (k0 + 63 > wq0) {
.LBB0_270:
	s_add_i32 s0, s4, 0xffffff80
	v_cmp_le_i32_e32 vcc, s0, v177
	s_and_saveexec_b64 s[90:91], vcc
	s_cbranch_execz .LBB0_276
	s_cmp_eq_u32 s63, 0
	s_cselect_b32 s97, 0xff800000, s6
	s_and_b32 s62, s63, 1
	s_mul_i32 s0, s62, 0x6400
	v_add_u32_e32 v181, s0, v178
	ds_read_b128 v[182:185], v181
	ds_read_b128 v[186:189], v181 offset:32
	ds_read_b128 v[190:193], v181 offset:12800
	ds_read_b128 v[194:197], v181 offset:12832
	ds_read_b128 v[198:201], v181 offset:64
	ds_read_b128 v[202:205], v181 offset:96
	ds_read_b128 v[206:209], v181 offset:12864
	ds_read_b128 v[210:213], v181 offset:12896
	v_sub_f32_e32 v66, 0, v180
	s_setprio 1
	v_mov_b32_e32 v67, v66
	v_mov_b64_e32 v[68:69], v[66:67]
	v_mov_b64_e32 v[70:71], v[66:67]
	v_mov_b64_e32 v[72:73], v[66:67]
	v_mov_b64_e32 v[74:75], v[66:67]
	v_mov_b64_e32 v[76:77], v[66:67]
	v_mov_b64_e32 v[78:79], v[66:67]
	v_mov_b64_e32 v[80:81], v[66:67]
	s_waitcnt vmcnt(16) lgkmcnt(7)
	s_nop 0
	v_mfma_f32_32x32x16_bf16 v[82:97], v[182:185], v[98:101], v[66:81]
	s_waitcnt lgkmcnt(5)
	v_mfma_f32_32x32x16_bf16 v[66:81], v[190:193], v[98:101], v[66:81]
	s_waitcnt vmcnt(15)
	v_mfma_f32_32x32x16_bf16 v[82:97], v[186:189], v[102:105], v[82:97]
	s_waitcnt lgkmcnt(4)
	v_mfma_f32_32x32x16_bf16 v[66:81], v[194:197], v[102:105], v[66:81]
	s_setprio 0
	ds_read_b128 v[182:185], v181 offset:128
	ds_read_b128 v[186:189], v181 offset:160
	ds_read_b128 v[190:193], v181 offset:12928
	ds_read_b128 v[194:197], v181 offset:12960
	s_setprio 1
	s_waitcnt vmcnt(14) lgkmcnt(7)
	v_mfma_f32_32x32x16_bf16 v[82:97], v[198:201], v[106:109], v[82:97]
	s_waitcnt lgkmcnt(5)
	v_mfma_f32_32x32x16_bf16 v[66:81], v[206:209], v[106:109], v[66:81]
	s_waitcnt vmcnt(13)
	v_mfma_f32_32x32x16_bf16 v[82:97], v[202:205], v[110:113], v[82:97]
	s_waitcnt lgkmcnt(4)
	v_mfma_f32_32x32x16_bf16 v[66:81], v[210:213], v[110:113], v[66:81]
	s_setprio 0
	ds_read_b128 v[198:201], v181 offset:192
	ds_read_b128 v[202:205], v181 offset:224
	ds_read_b128 v[206:209], v181 offset:12992
	ds_read_b128 v[210:213], v181 offset:13024
	s_setprio 1
	s_waitcnt vmcnt(12) lgkmcnt(7)
	v_mfma_f32_32x32x16_bf16 v[82:97], v[182:185], v[114:117], v[82:97]
	s_waitcnt lgkmcnt(5)
	v_mfma_f32_32x32x16_bf16 v[66:81], v[190:193], v[114:117], v[66:81]
	s_waitcnt vmcnt(11)
	v_mfma_f32_32x32x16_bf16 v[82:97], v[186:189], v[118:121], v[82:97]
	s_waitcnt lgkmcnt(4)
	v_mfma_f32_32x32x16_bf16 v[66:81], v[194:197], v[118:121], v[66:81]
	s_setprio 0
	ds_read_b128 v[182:185], v181 offset:256
	ds_read_b128 v[186:189], v181 offset:288
	ds_read_b128 v[190:193], v181 offset:13056
	ds_read_b128 v[194:197], v181 offset:13088
	s_setprio 1
	s_waitcnt vmcnt(10) lgkmcnt(7)
	v_mfma_f32_32x32x16_bf16 v[82:97], v[198:201], v[122:125], v[82:97]
	s_waitcnt lgkmcnt(5)
	v_mfma_f32_32x32x16_bf16 v[66:81], v[206:209], v[122:125], v[66:81]
	s_waitcnt vmcnt(9)
	v_mfma_f32_32x32x16_bf16 v[82:97], v[202:205], v[126:129], v[82:97]
	s_waitcnt lgkmcnt(4)
	v_mfma_f32_32x32x16_bf16 v[66:81], v[210:213], v[126:129], v[66:81]
	s_setprio 0
	ds_read_b128 v[198:201], v181 offset:320
	ds_read_b128 v[202:205], v181 offset:352
	ds_read_b128 v[206:209], v181 offset:13120
	ds_read_b128 v[210:213], v181 offset:13152
	s_setprio 1
	s_waitcnt vmcnt(8) lgkmcnt(7)
	v_mfma_f32_32x32x16_bf16 v[82:97], v[182:185], v[130:133], v[82:97]
	s_waitcnt lgkmcnt(5)
	v_mfma_f32_32x32x16_bf16 v[66:81], v[190:193], v[130:133], v[66:81]
	s_waitcnt vmcnt(7)
	v_mfma_f32_32x32x16_bf16 v[82:97], v[186:189], v[134:137], v[82:97]
	s_waitcnt lgkmcnt(4)
	v_mfma_f32_32x32x16_bf16 v[66:81], v[194:197], v[134:137], v[66:81]
	s_setprio 0
	s_setprio 1
	s_waitcnt vmcnt(6) lgkmcnt(3)
	v_mfma_f32_32x32x16_bf16 v[82:97], v[198:201], v[138:141], v[82:97]
	s_waitcnt lgkmcnt(1)
	v_mfma_f32_32x32x16_bf16 v[66:81], v[206:209], v[138:141], v[66:81]
	s_waitcnt vmcnt(5)
	v_mfma_f32_32x32x16_bf16 v[82:97], v[202:205], v[142:145], v[82:97]
	s_waitcnt lgkmcnt(0)
	v_mfma_f32_32x32x16_bf16 v[66:81], v[210:213], v[142:145], v[66:81]
	s_setprio 0
	s_add_i32 s0, s4, 0xffffffbf
	v_cmp_gt_i32_e32 vcc, s0, v167
	s_and_saveexec_b64 s[0:1], vcc
	s_cbranch_execz .LBB0_273
; template <int DQK, int KROW, bool BIAS, bool MAPS2>
; DI void attn_core(const int t, const u16* __restrict__ Q, int ldq, const u16* __restrict__ Kp, int ldk, const u16* __restrict__ Vt, int q0,
;                   char* lds, const float* lut, float b31, f32x16 (&o)[4], float& l_out) {
;     ...
;       if (k0 + 63 > wq0) {
; #pragma unroll
;         for (int k2 = 0; k2 < 2; ++k2)
; #pragma unroll
;           for (int i = 0; i < 16; ++i) {
;             const int key = k0 + 32 * k2 + (i & 3) + 8 * (i >> 2) + 4 * hf;
;             if (key > qrow) s[k2][i] = -INFINITY;
;           }
;       }
	v_add_u32_e32 v181, s4, v176
	v_add_u32_e32 v182, 0xffffff80, v181
	v_cmp_gt_i32_e32 vcc, v182, v170
	s_nop 1
	v_cndmask_b32_e32 v183, v82, v230, vcc
	v_cmp_lt_i32_e32 vcc, v182, v170
	v_add_u32_e32 v182, 0xffffff82, v181
	s_nop 0
	v_cndmask_b32_e32 v82, v183, v82, vcc
	v_cndmask_b32_e32 v83, v230, v83, vcc
	v_cmp_le_i32_e32 vcc, v182, v170
	v_add_u32_e32 v182, 0xffffff83, v181
	s_nop 0
	v_cndmask_b32_e32 v84, v230, v84, vcc
	v_cmp_le_i32_e32 vcc, v182, v170
	v_add_u32_e32 v182, 0xffffff88, v181
	s_nop 0
	v_cndmask_b32_e32 v85, v230, v85, vcc
	v_cmp_le_i32_e32 vcc, v182, v170
	v_add_u32_e32 v182, 0xffffff89, v181
	s_nop 0
	v_cndmask_b32_e32 v86, v230, v86, vcc
	v_cmp_le_i32_e32 vcc, v182, v170
	v_add_u32_e32 v182, 0xffffff8a, v181
	s_nop 0
	v_cndmask_b32_e32 v87, v230, v87, vcc
	v_cmp_le_i32_e32 vcc, v182, v170
	v_add_u32_e32 v182, 0xffffff8b, v181
	s_nop 0
	v_cndmask_b32_e32 v88, v230, v88, vcc
	v_cmp_le_i32_e32 vcc, v182, v170
	v_add_u32_e32 v182, 0xffffff90, v181
	s_nop 0
	v_cndmask_b32_e32 v89, v230, v89, vcc
	v_cmp_le_i32_e32 vcc, v182, v170
	v_add_u32_e32 v182, 0xffffff91, v181
	s_nop 0
	v_cndmask_b32_e32 v90, v230, v90, vcc
	v_cmp_le_i32_e32 vcc, v182, v170
	v_add_u32_e32 v182, 0xffffff92, v181
	s_nop 0
	v_cndmask_b32_e32 v91, v230, v91, vcc
	v_cmp_le_i32_e32 vcc, v182, v170
	v_add_u32_e32 v182, 0xffffff93, v181
	s_nop 0
	v_cndmask_b32_e32 v92, v230, v92, vcc
	v_cmp_le_i32_e32 vcc, v182, v170
	v_add_u32_e32 v182, 0xffffff98, v181
	s_nop 0
	v_cndmask_b32_e32 v93, v230, v93, vcc
	v_cmp_le_i32_e32 vcc, v182, v170
	v_add_u32_e32 v182, 0xffffff99, v181
	s_nop 0
	v_cndmask_b32_e32 v94, v230, v94, vcc
	v_cmp_le_i32_e32 vcc, v182, v170
	v_add_u32_e32 v182, 0xffffff9a, v181
	s_nop 0
	v_cndmask_b32_e32 v95, v230, v95, vcc
	v_cmp_le_i32_e32 vcc, v182, v170
	v_add_u32_e32 v182, 0xffffff9b, v181
	s_nop 0
	v_cndmask_b32_e32 v96, v230, v96, vcc
	v_cmp_le_i32_e32 vcc, v182, v170
	v_add_u32_e32 v182, 0xffffffa0, v181
	s_nop 0
	v_cndmask_b32_e32 v97, v230, v97, vcc
	v_cmp_le_i32_e32 vcc, v182, v170
	v_add_u32_e32 v182, 0xffffffa1, v181
	s_nop 0
	v_cndmask_b32_e32 v66, v230, v66, vcc
	v_cmp_le_i32_e32 vcc, v182, v170
	v_add_u32_e32 v182, 0xffffffa2, v181
	s_nop 0
	v_cndmask_b32_e32 v67, v230, v67, vcc
	v_cmp_le_i32_e32 vcc, v182, v170
	v_add_u32_e32 v182, 0xffffffa3, v181
	s_nop 0
	v_cndmask_b32_e32 v68, v230, v68, vcc
	v_cmp_le_i32_e32 vcc, v182, v170
	v_add_u32_e32 v182, 0xffffffa8, v181
	s_nop 0
	v_cndmask_b32_e32 v69, v230, v69, vcc
	v_cmp_le_i32_e32 vcc, v182, v170
	v_add_u32_e32 v182, 0xffffffa9, v181
	s_nop 0
	v_cndmask_b32_e32 v70, v230, v70, vcc
	v_cmp_le_i32_e32 vcc, v182, v170
	v_add_u32_e32 v182, 0xffffffaa, v181
	s_nop 0
	v_cndmask_b32_e32 v71, v230, v71, vcc
	v_cmp_le_i32_e32 vcc, v182, v170
	v_add_u32_e32 v182, 0xffffffab, v181
	s_nop 0
	v_cndmask_b32_e32 v72, v230, v72, vcc
	v_cmp_le_i32_e32 vcc, v182, v170
	v_add_u32_e32 v182, 0xffffffb0, v181
	s_nop 0
	v_cndmask_b32_e32 v73, v230, v73, vcc
	v_cmp_le_i32_e32 vcc, v182, v170
	v_add_u32_e32 v182, 0xffffffb1, v181
	s_nop 0
	v_cndmask_b32_e32 v74, v230, v74, vcc
	v_cmp_le_i32_e32 vcc, v182, v170
	v_add_u32_e32 v182, 0xffffffb2, v181
	s_nop 0
	v_cndmask_b32_e32 v75, v230, v75, vcc
	v_cmp_le_i32_e32 vcc, v182, v170
	v_add_u32_e32 v182, 0xffffffb3, v181
	s_nop 0
	v_cndmask_b32_e32 v76, v230, v76, vcc
	v_cmp_le_i32_e32 vcc, v182, v170
	v_add_u32_e32 v182, 0xffffffb8, v181
	s_nop 0
	v_cndmask_b32_e32 v77, v230, v77, vcc
	v_cmp_le_i32_e32 vcc, v182, v170
	v_add_u32_e32 v182, 0xffffffb9, v181
	s_nop 0
	v_cndmask_b32_e32 v78, v230, v78, vcc
	v_cmp_le_i32_e32 vcc, v182, v170
	v_add_u32_e32 v182, 0xffffffba, v181
	v_add_u32_e32 v181, 0xffffffbb, v181
	v_cndmask_b32_e32 v79, v230, v79, vcc
	v_cmp_le_i32_e32 vcc, v182, v170
	s_nop 1
	v_cndmask_b32_e32 v80, v230, v80, vcc
	v_cmp_le_i32_e32 vcc, v181, v170
	s_nop 1
	v_cndmask_b32_e32 v81, v230, v81, vcc
